# U pass (PEER partial dots) rewritten by hand: VOP3P dot4 without accumulator zeroing moves, reduce-scatter row sums instead of 3 DPP adds per row, own load pipeline
# speedup vs baseline: 1.0094x; 1.0094x over previous
; template <bool VPASS>
; __device__ __forceinline__ PeerVisit visit_load(const unsigned char* ws, const unsigned char* FQc, int tok, int lane) {
;     PeerVisit v; const int pg = lane >> 3;
;     const u32x4* ep = (const u32x4*)((const int*)(ws + WS_SELE) + (size_t)tok * 128 + pg * 16);
; #pragma unroll
;     for (int q = 0; q < 4; ++q) v.e[q] = ep[q];
;     if (VPASS) { v.x = *(const u32x4*)(ws + WS_CFQ + (size_t)tok * 128 + pg * 16); v.x2 = v.x; v.sc = ((const float*)(ws + WS_CS))[2 * tok]; v.cs = ((const int*)(ws + WS_CS))[2 * tok + 1]; }
;     else { const u32x4* fp = (const u32x4*)(FQc + (size_t)tok * D + (lane & 7) * 32); v.x = fp[0]; v.x2 = fp[1]; v.sc = 0.f; v.cs = 0; }
;     return v;
; }
; template <bool VPASS>
; __device__ __forceinline__ void peer_pass(Frame& F, int c, int rank, int nblk) {
;     const unsigned char* T = F.ws + (VPASS ? WS_PV : WS_PU) + (size_t)c * 16384 * 128; const unsigned char* FQc = F.ws + WS_FQ + c * 256;
;     int* PD = (int*)(F.ws + WS_PD) + (size_t)c * NTOK * 128; bf16* PO = (bf16*)(F.ws + WS_PO) + c * 256;
;     const int t0 = rank * NWAVES + F.wave, step = nblk * NWAVES;
;     if (t0 >= NTOK) return;
;     const int nvis = (NTOK - t0 + step - 1) / step;
;     int lane = F.lane; asm volatile("" : "+v"(lane));
;     PeerVisit va = visit_load<VPASS>(F.ws, FQc, t0, lane), vb = va;
;     u32x4 wa[16], wb[16];
;     rows16_load(wa, T, va, lane);
;     if (nvis > 1) vb = visit_load<VPASS>(F.ws, FQc, t0 + step, lane);
; #pragma unroll 1
;     for (int v = 0; v < nvis; v += 2) {
;         const int tok = t0 + v * step;
;         asm volatile("" : "+v"(lane));
;         PeerVisit vn = va;
;         if (v + 1 < nvis) rows16_load(wb, T, vb, lane);
;         if (v + 2 < nvis) vn = visit_load<VPASS>(F.ws, FQc, tok + 2 * step, lane);
;         if (VPASS) v_compute(wa, va, PO + (size_t)tok * D, lane); else u_compute(wa, va, PD + (size_t)tok * 128, lane);
;         if (v + 1 < nvis) {
;             PeerVisit vm = vb;
;             if (v + 2 < nvis) rows16_load(wa, T, vn, lane);
;             if (v + 3 < nvis) vm = visit_load<VPASS>(F.ws, FQc, tok + 3 * step, lane);
;             if (VPASS) v_compute(wb, vb, PO + (size_t)(tok + step) * D, lane); else u_compute(wb, vb, PD + (size_t)(tok + step) * 128, lane);
;             vb = vm;
;         }
;         va = vn;
;     }
; }
.LBB0_2001:
	s_nop 0
	v_readfirstlane_b32 s38, v10
	s_ashr_i32 s39, s38, 31
	s_lshl_b32 s72, s38, 8
	s_lshl_b64 s[74:75], s[38:39], 21
	s_ashr_i32 s73, s72, 31
	s_waitcnt lgkmcnt(0)
	v_readfirstlane_b32 s92, v8
	s_add_u32 s3, s56, 0x1e000000
	v_readfirstlane_b32 s91, v9
	s_addc_u32 s55, s57, 0
	s_lshl_b32 s40, s92, 3
	s_add_i32 s70, s40, s95
	s_lshl_b32 s90, s91, 3
	s_cmp_lt_i32 s70, 0x8000
	s_mov_b32 s68, s95
	s_cselect_b64 s[76:77], -1, 0
	s_cmpk_gt_i32 s70, 0x7fff
	v_mbcnt_lo_u32_b32 v188, -1, 0
	v_mbcnt_hi_u32_b32 v188, -1, v188
	s_cbranch_scc1 .LBB0_2020
	s_mov_b32 s82, 0xf0f0f0f0
	s_mov_b32 s83, 0xf0f0f0f0
	s_mov_b32 s84, 0xcccccccc
	s_mov_b32 s85, 0xcccccccc
	s_mov_b32 s86, 0xaaaaaaaa
	s_mov_b32 s87, 0xaaaaaaaa
	v_and_b32_e32 v3, 7, v188
	s_mov_b32 s61, 0xf0f0f0f
	s_mov_b32 s62, 0xf0f0f0f0
	v_lshrrev_b32_e32 v0, 3, v188
	v_and_b32_e32 v1, 7, v188
	v_lshlrev_b32_e32 v0, 6, v0
	v_lshlrev_b32_e32 v2, 5, v1
	v_lshlrev_b32_e32 v1, 4, v1
	v_lshl_add_u32 v3, v3, 2, v0
	s_mov_b32 s39, s90
	s_mov_b32 s93, s70
	s_lshl_b32 s48, s90, 9
	s_lshl_b32 s49, s90, 11
	s_lshl_b32 s63, s38, 21
	s_add_u32 s40, s56, s63
	s_addc_u32 s41, s57, 0
	s_add_u32 s40, s40, 0x8000000
	s_addc_u32 s41, s41, 0
	s_lshl_b32 s63, s70, 9
	s_add_u32 s42, s56, s63
	s_addc_u32 s43, s57, 0
	s_add_u32 s42, s42, 0xc200000
	s_addc_u32 s43, s43, 0
	s_lshl_b32 s71, s38, 24
	s_add_u32 s71, s71, s63
	s_add_u32 s46, s56, s71
	s_addc_u32 s47, s57, 0
	s_add_u32 s46, s46, 0x1e000000
	s_addc_u32 s47, s47, 0
	s_lshl_b32 s63, s70, 11
	s_lshl_b32 s71, s38, 8
	s_add_u32 s63, s63, s71
	s_add_u32 s44, s56, s63
	s_addc_u32 s45, s57, 0
	s_add_u32 s44, s44, 0x18000000
	s_addc_u32 s45, s45, 0
	s_mov_b32 s38, s70
	global_load_dwordx4 v[132:135], v0, s[42:43]
	global_load_dwordx4 v[136:139], v0, s[42:43] offset:16
	global_load_dwordx4 v[140:143], v0, s[42:43] offset:32
	global_load_dwordx4 v[144:147], v0, s[42:43] offset:48
	global_load_dwordx4 v[164:167], v2, s[44:45]
	global_load_dwordx4 v[168:171], v2, s[44:45] offset:16
	s_waitcnt vmcnt(0)
	v_lshl_add_u32 v180, v132, 7, v1
	v_lshl_add_u32 v181, v133, 7, v1
	v_lshl_add_u32 v182, v134, 7, v1
	v_lshl_add_u32 v183, v135, 7, v1
	v_lshl_add_u32 v184, v136, 7, v1
	v_lshl_add_u32 v185, v137, 7, v1
	v_lshl_add_u32 v186, v138, 7, v1
	v_lshl_add_u32 v187, v139, 7, v1
	v_lshl_add_u32 v188, v140, 7, v1
	v_lshl_add_u32 v189, v141, 7, v1
	v_lshl_add_u32 v190, v142, 7, v1
	v_lshl_add_u32 v191, v143, 7, v1
	v_lshl_add_u32 v192, v144, 7, v1
	v_lshl_add_u32 v193, v145, 7, v1
	v_lshl_add_u32 v194, v146, 7, v1
	v_lshl_add_u32 v195, v147, 7, v1
	s_add_i32 s38, s38, s39
	s_cmp_lt_i32 s38, 0x8000
	s_cselect_b32 s63, s48, 0
	s_cselect_b32 s71, s49, 0
	s_add_u32 s42, s42, s63
	s_addc_u32 s43, s43, 0
	s_add_u32 s44, s44, s71
	s_addc_u32 s45, s45, 0
	global_load_dwordx4 v[132:135], v0, s[42:43]
	global_load_dwordx4 v[136:139], v0, s[42:43] offset:16
	global_load_dwordx4 v[140:143], v0, s[42:43] offset:32
	global_load_dwordx4 v[144:147], v0, s[42:43] offset:48
	global_load_dwordx4 v[4:7], v180, s[40:41]
	global_load_dwordx4 v[8:11], v181, s[40:41]
	global_load_dwordx4 v[12:15], v182, s[40:41]
	global_load_dwordx4 v[16:19], v183, s[40:41]
	global_load_dwordx4 v[20:23], v184, s[40:41]
	global_load_dwordx4 v[24:27], v185, s[40:41]
	global_load_dwordx4 v[28:31], v186, s[40:41]
	global_load_dwordx4 v[32:35], v187, s[40:41]
	global_load_dwordx4 v[36:39], v188, s[40:41]
	global_load_dwordx4 v[40:43], v189, s[40:41]
	global_load_dwordx4 v[44:47], v190, s[40:41]
	global_load_dwordx4 v[48:51], v191, s[40:41]
	global_load_dwordx4 v[52:55], v192, s[40:41]
	global_load_dwordx4 v[56:59], v193, s[40:41]
	global_load_dwordx4 v[60:63], v194, s[40:41]
	global_load_dwordx4 v[64:67], v195, s[40:41]
	global_load_dwordx4 v[172:175], v2, s[44:45]
	global_load_dwordx4 v[176:179], v2, s[44:45] offset:16
	global_load_dword v228, v0, s[42:43]
	global_load_dword v228, v0, s[42:43]
	s_waitcnt vmcnt(20)
.Lmy_u_loop:
	v_lshl_add_u32 v180, v132, 7, v1
	v_lshl_add_u32 v181, v133, 7, v1
	v_lshl_add_u32 v182, v134, 7, v1
	v_lshl_add_u32 v183, v135, 7, v1
	v_lshl_add_u32 v184, v136, 7, v1
	v_lshl_add_u32 v185, v137, 7, v1
	v_lshl_add_u32 v186, v138, 7, v1
	v_lshl_add_u32 v187, v139, 7, v1
	v_lshl_add_u32 v188, v140, 7, v1
	v_lshl_add_u32 v189, v141, 7, v1
	v_lshl_add_u32 v190, v142, 7, v1
	v_lshl_add_u32 v191, v143, 7, v1
	v_lshl_add_u32 v192, v144, 7, v1
	v_lshl_add_u32 v193, v145, 7, v1
	v_lshl_add_u32 v194, v146, 7, v1
	v_lshl_add_u32 v195, v147, 7, v1
	s_add_i32 s38, s38, s39
	s_cmp_lt_i32 s38, 0x8000
	s_cselect_b32 s63, s48, 0
	s_cselect_b32 s71, s49, 0
	s_add_u32 s42, s42, s63
	s_addc_u32 s43, s43, 0
	s_add_u32 s44, s44, s71
	s_addc_u32 s45, s45, 0
	global_load_dwordx4 v[132:135], v0, s[42:43]
	global_load_dwordx4 v[136:139], v0, s[42:43] offset:16
	global_load_dwordx4 v[140:143], v0, s[42:43] offset:32
	global_load_dwordx4 v[144:147], v0, s[42:43] offset:48
	global_load_dwordx4 v[68:71], v180, s[40:41]
	global_load_dwordx4 v[72:75], v181, s[40:41]
	global_load_dwordx4 v[76:79], v182, s[40:41]
	global_load_dwordx4 v[80:83], v183, s[40:41]
	global_load_dwordx4 v[84:87], v184, s[40:41]
	global_load_dwordx4 v[88:91], v185, s[40:41]
	global_load_dwordx4 v[92:95], v186, s[40:41]
	global_load_dwordx4 v[96:99], v187, s[40:41]
	global_load_dwordx4 v[100:103], v188, s[40:41]
	global_load_dwordx4 v[104:107], v189, s[40:41]
	global_load_dwordx4 v[108:111], v190, s[40:41]
	global_load_dwordx4 v[112:115], v191, s[40:41]
	global_load_dwordx4 v[116:119], v192, s[40:41]
	global_load_dwordx4 v[120:123], v193, s[40:41]
	global_load_dwordx4 v[124:127], v194, s[40:41]
	global_load_dwordx4 v[128:131], v195, s[40:41]
	s_waitcnt vmcnt(38)
; __device__ __forceinline__ void u_compute(const u32x4 (&w)[16], const PeerVisit& v, int* pd, int lane) {
;     ...
;     for (int it = 0; it < 16; ++it) {
;         int tl = 0, th = 0;
;         tl = __builtin_amdgcn_sdot4((int)(w[it].x & 0x0F0F0F0Fu), (int)v.x.x, tl, false);  th = __builtin_amdgcn_sdot4((int)(w[it].x & 0xF0F0F0F0u), (int)v.x.y, th, false);
;         tl = __builtin_amdgcn_sdot4((int)(w[it].y & 0x0F0F0F0Fu), (int)v.x.z, tl, false);  th = __builtin_amdgcn_sdot4((int)(w[it].y & 0xF0F0F0F0u), (int)v.x.w, th, false);
;         tl = __builtin_amdgcn_sdot4((int)(w[it].z & 0x0F0F0F0Fu), (int)v.x2.x, tl, false); th = __builtin_amdgcn_sdot4((int)(w[it].z & 0xF0F0F0F0u), (int)v.x2.y, th, false);
;         tl = __builtin_amdgcn_sdot4((int)(w[it].w & 0x0F0F0F0Fu), (int)v.x2.z, tl, false); th = __builtin_amdgcn_sdot4((int)(w[it].w & 0xF0F0F0F0u), (int)v.x2.w, th, false);
;         const int t = tl * 16 + th;
;         d[it] = dpp_add8(t);
;     }
	v_and_b32_e32 v180, s61, v4
	v_and_b32_e32 v4, s62, v4
	v_and_b32_e32 v181, s61, v5
	v_and_b32_e32 v5, s62, v5
	v_and_b32_e32 v182, s61, v6
	v_and_b32_e32 v6, s62, v6
	v_and_b32_e32 v183, s61, v7
	v_and_b32_e32 v7, s62, v7
	v_dot4_i32_i8 v196, v180, v164, 0
	v_dot4_i32_i8 v197, v4, v165, 0
	v_dot4_i32_i8 v196, v181, v166, v196
	v_dot4_i32_i8 v197, v5, v167, v197
	v_dot4_i32_i8 v196, v182, v168, v196
	v_dot4_i32_i8 v197, v6, v169, v197
	v_dot4_i32_i8 v196, v183, v170, v196
	v_dot4_i32_i8 v197, v7, v171, v197
	v_and_b32_e32 v188, s61, v8
	v_and_b32_e32 v8, s62, v8
	v_and_b32_e32 v189, s61, v9
	v_and_b32_e32 v9, s62, v9
	v_lshl_add_u32 v148, v196, 4, v197
	v_and_b32_e32 v190, s61, v10
	v_and_b32_e32 v10, s62, v10
	v_and_b32_e32 v191, s61, v11
	v_and_b32_e32 v11, s62, v11
	v_dot4_i32_i8 v198, v188, v164, 0
	v_dot4_i32_i8 v199, v8, v165, 0
	v_dot4_i32_i8 v198, v189, v166, v198
	v_dot4_i32_i8 v199, v9, v167, v199
	v_dot4_i32_i8 v198, v190, v168, v198
	v_dot4_i32_i8 v199, v10, v169, v199
	v_dot4_i32_i8 v198, v191, v170, v198
	v_dot4_i32_i8 v199, v11, v171, v199
	s_waitcnt vmcnt(36)
	v_and_b32_e32 v180, s61, v12
	v_and_b32_e32 v12, s62, v12
	v_and_b32_e32 v181, s61, v13
	v_and_b32_e32 v13, s62, v13
	v_lshl_add_u32 v149, v198, 4, v199
	v_and_b32_e32 v182, s61, v14
	v_and_b32_e32 v14, s62, v14
	v_and_b32_e32 v183, s61, v15
	v_and_b32_e32 v15, s62, v15
	v_dot4_i32_i8 v196, v180, v164, 0
	v_dot4_i32_i8 v197, v12, v165, 0
	v_dot4_i32_i8 v196, v181, v166, v196
	v_dot4_i32_i8 v197, v13, v167, v197
	v_dot4_i32_i8 v196, v182, v168, v196
	v_dot4_i32_i8 v197, v14, v169, v197
	v_dot4_i32_i8 v196, v183, v170, v196
	v_dot4_i32_i8 v197, v15, v171, v197
	v_and_b32_e32 v188, s61, v16
	v_and_b32_e32 v16, s62, v16
	v_and_b32_e32 v189, s61, v17
	v_and_b32_e32 v17, s62, v17
	v_lshl_add_u32 v150, v196, 4, v197
	v_and_b32_e32 v190, s61, v18
	v_and_b32_e32 v18, s62, v18
	v_and_b32_e32 v191, s61, v19
	v_and_b32_e32 v19, s62, v19
	v_dot4_i32_i8 v198, v188, v164, 0
	v_dot4_i32_i8 v199, v16, v165, 0
	v_dot4_i32_i8 v198, v189, v166, v198
	v_dot4_i32_i8 v199, v17, v167, v199
	v_dot4_i32_i8 v198, v190, v168, v198
	v_dot4_i32_i8 v199, v18, v169, v199
	v_dot4_i32_i8 v198, v191, v170, v198
	v_dot4_i32_i8 v199, v19, v171, v199
	s_waitcnt vmcnt(34)
	v_and_b32_e32 v180, s61, v20
	v_and_b32_e32 v20, s62, v20
	v_and_b32_e32 v181, s61, v21
	v_and_b32_e32 v21, s62, v21
	v_lshl_add_u32 v151, v198, 4, v199
	v_and_b32_e32 v182, s61, v22
	v_and_b32_e32 v22, s62, v22
	v_and_b32_e32 v183, s61, v23
	v_and_b32_e32 v23, s62, v23
	v_dot4_i32_i8 v196, v180, v164, 0
	v_dot4_i32_i8 v197, v20, v165, 0
	v_dot4_i32_i8 v196, v181, v166, v196
	v_dot4_i32_i8 v197, v21, v167, v197
	v_dot4_i32_i8 v196, v182, v168, v196
	v_dot4_i32_i8 v197, v22, v169, v197
	v_dot4_i32_i8 v196, v183, v170, v196
	v_dot4_i32_i8 v197, v23, v171, v197
	v_and_b32_e32 v188, s61, v24
	v_and_b32_e32 v24, s62, v24
	v_and_b32_e32 v189, s61, v25
	v_and_b32_e32 v25, s62, v25
	v_lshl_add_u32 v152, v196, 4, v197
	v_and_b32_e32 v190, s61, v26
	v_and_b32_e32 v26, s62, v26
	v_and_b32_e32 v191, s61, v27
	v_and_b32_e32 v27, s62, v27
	v_dot4_i32_i8 v198, v188, v164, 0
	v_dot4_i32_i8 v199, v24, v165, 0
	v_dot4_i32_i8 v198, v189, v166, v198
	v_dot4_i32_i8 v199, v25, v167, v199
	v_dot4_i32_i8 v198, v190, v168, v198
	v_dot4_i32_i8 v199, v26, v169, v199
	v_dot4_i32_i8 v198, v191, v170, v198
	v_dot4_i32_i8 v199, v27, v171, v199
	s_waitcnt vmcnt(32)
	v_and_b32_e32 v180, s61, v28
	v_and_b32_e32 v28, s62, v28
	v_and_b32_e32 v181, s61, v29
	v_and_b32_e32 v29, s62, v29
	v_lshl_add_u32 v153, v198, 4, v199
	v_and_b32_e32 v182, s61, v30
	v_and_b32_e32 v30, s62, v30
	v_and_b32_e32 v183, s61, v31
	v_and_b32_e32 v31, s62, v31
	v_dot4_i32_i8 v196, v180, v164, 0
	v_dot4_i32_i8 v197, v28, v165, 0
	v_dot4_i32_i8 v196, v181, v166, v196
	v_dot4_i32_i8 v197, v29, v167, v197
	v_dot4_i32_i8 v196, v182, v168, v196
	v_dot4_i32_i8 v197, v30, v169, v197
	v_dot4_i32_i8 v196, v183, v170, v196
	v_dot4_i32_i8 v197, v31, v171, v197
	v_and_b32_e32 v188, s61, v32
	v_and_b32_e32 v32, s62, v32
	v_and_b32_e32 v189, s61, v33
	v_and_b32_e32 v33, s62, v33
	v_lshl_add_u32 v154, v196, 4, v197
	v_and_b32_e32 v190, s61, v34
	v_and_b32_e32 v34, s62, v34
	v_and_b32_e32 v191, s61, v35
	v_and_b32_e32 v35, s62, v35
	v_dot4_i32_i8 v198, v188, v164, 0
	v_dot4_i32_i8 v199, v32, v165, 0
	v_dot4_i32_i8 v198, v189, v166, v198
	v_dot4_i32_i8 v199, v33, v167, v199
	v_dot4_i32_i8 v198, v190, v168, v198
	v_dot4_i32_i8 v199, v34, v169, v199
	v_dot4_i32_i8 v198, v191, v170, v198
	v_dot4_i32_i8 v199, v35, v171, v199
	s_waitcnt vmcnt(30)
	v_and_b32_e32 v180, s61, v36
	v_and_b32_e32 v36, s62, v36
	v_and_b32_e32 v181, s61, v37
	v_and_b32_e32 v37, s62, v37
	v_lshl_add_u32 v155, v198, 4, v199
	v_and_b32_e32 v182, s61, v38
	v_and_b32_e32 v38, s62, v38
	v_and_b32_e32 v183, s61, v39
	v_and_b32_e32 v39, s62, v39
	v_dot4_i32_i8 v196, v180, v164, 0
	v_dot4_i32_i8 v197, v36, v165, 0
	v_dot4_i32_i8 v196, v181, v166, v196
	v_dot4_i32_i8 v197, v37, v167, v197
	v_dot4_i32_i8 v196, v182, v168, v196
	v_dot4_i32_i8 v197, v38, v169, v197
	v_dot4_i32_i8 v196, v183, v170, v196
	v_dot4_i32_i8 v197, v39, v171, v197
	v_and_b32_e32 v188, s61, v40
	v_and_b32_e32 v40, s62, v40
	v_and_b32_e32 v189, s61, v41
	v_and_b32_e32 v41, s62, v41
	v_lshl_add_u32 v156, v196, 4, v197
	v_and_b32_e32 v190, s61, v42
	v_and_b32_e32 v42, s62, v42
	v_and_b32_e32 v191, s61, v43
	v_and_b32_e32 v43, s62, v43
	v_dot4_i32_i8 v198, v188, v164, 0
	v_dot4_i32_i8 v199, v40, v165, 0
	v_dot4_i32_i8 v198, v189, v166, v198
	v_dot4_i32_i8 v199, v41, v167, v199
	v_dot4_i32_i8 v198, v190, v168, v198
	v_dot4_i32_i8 v199, v42, v169, v199
	v_dot4_i32_i8 v198, v191, v170, v198
	v_dot4_i32_i8 v199, v43, v171, v199
	s_waitcnt vmcnt(28)
; __device__ __forceinline__ void u_compute(const u32x4 (&w)[16], const PeerVisit& v, int* pd, int lane) {
;     ...
;     for (int it = 0; it < 16; ++it) {
;         int tl = 0, th = 0;
;         tl = __builtin_amdgcn_sdot4((int)(w[it].x & 0x0F0F0F0Fu), (int)v.x.x, tl, false);  th = __builtin_amdgcn_sdot4((int)(w[it].x & 0xF0F0F0F0u), (int)v.x.y, th, false);
;         tl = __builtin_amdgcn_sdot4((int)(w[it].y & 0x0F0F0F0Fu), (int)v.x.z, tl, false);  th = __builtin_amdgcn_sdot4((int)(w[it].y & 0xF0F0F0F0u), (int)v.x.w, th, false);
;         tl = __builtin_amdgcn_sdot4((int)(w[it].z & 0x0F0F0F0Fu), (int)v.x2.x, tl, false); th = __builtin_amdgcn_sdot4((int)(w[it].z & 0xF0F0F0F0u), (int)v.x2.y, th, false);
;         tl = __builtin_amdgcn_sdot4((int)(w[it].w & 0x0F0F0F0Fu), (int)v.x2.z, tl, false); th = __builtin_amdgcn_sdot4((int)(w[it].w & 0xF0F0F0F0u), (int)v.x2.w, th, false);
;         const int t = tl * 16 + th;
;         d[it] = dpp_add8(t);
;     }
;     int v0 = d[0], v1 = d[8];
; #pragma unroll
;     for (int it = 1; it < 8; ++it) { v0 = (sub == it) ? d[it] : v0; v1 = (sub == it) ? d[8 + it] : v1; }
;     __builtin_nontemporal_store(v0, pd + pg * 16 + sub); __builtin_nontemporal_store(v1, pd + pg * 16 + 8 + sub);
	v_and_b32_e32 v180, s61, v44
	v_and_b32_e32 v44, s62, v44
	v_and_b32_e32 v181, s61, v45
	v_and_b32_e32 v45, s62, v45
	v_lshl_add_u32 v157, v198, 4, v199
	v_and_b32_e32 v182, s61, v46
	v_and_b32_e32 v46, s62, v46
	v_and_b32_e32 v183, s61, v47
	v_and_b32_e32 v47, s62, v47
	v_dot4_i32_i8 v196, v180, v164, 0
	v_dot4_i32_i8 v197, v44, v165, 0
	v_dot4_i32_i8 v196, v181, v166, v196
	v_dot4_i32_i8 v197, v45, v167, v197
	v_dot4_i32_i8 v196, v182, v168, v196
	v_dot4_i32_i8 v197, v46, v169, v197
	v_dot4_i32_i8 v196, v183, v170, v196
	v_dot4_i32_i8 v197, v47, v171, v197
	v_and_b32_e32 v188, s61, v48
	v_and_b32_e32 v48, s62, v48
	v_and_b32_e32 v189, s61, v49
	v_and_b32_e32 v49, s62, v49
	v_lshl_add_u32 v158, v196, 4, v197
	v_and_b32_e32 v190, s61, v50
	v_and_b32_e32 v50, s62, v50
	v_and_b32_e32 v191, s61, v51
	v_and_b32_e32 v51, s62, v51
	v_dot4_i32_i8 v198, v188, v164, 0
	v_dot4_i32_i8 v199, v48, v165, 0
	v_dot4_i32_i8 v198, v189, v166, v198
	v_dot4_i32_i8 v199, v49, v167, v199
	v_dot4_i32_i8 v198, v190, v168, v198
	v_dot4_i32_i8 v199, v50, v169, v199
	v_dot4_i32_i8 v198, v191, v170, v198
	v_dot4_i32_i8 v199, v51, v171, v199
	s_waitcnt vmcnt(26)
	v_and_b32_e32 v180, s61, v52
	v_and_b32_e32 v52, s62, v52
	v_and_b32_e32 v181, s61, v53
	v_and_b32_e32 v53, s62, v53
	v_lshl_add_u32 v159, v198, 4, v199
	v_and_b32_e32 v182, s61, v54
	v_and_b32_e32 v54, s62, v54
	v_and_b32_e32 v183, s61, v55
	v_and_b32_e32 v55, s62, v55
	v_dot4_i32_i8 v196, v180, v164, 0
	v_dot4_i32_i8 v197, v52, v165, 0
	v_dot4_i32_i8 v196, v181, v166, v196
	v_dot4_i32_i8 v197, v53, v167, v197
	v_dot4_i32_i8 v196, v182, v168, v196
	v_dot4_i32_i8 v197, v54, v169, v197
	v_dot4_i32_i8 v196, v183, v170, v196
	v_dot4_i32_i8 v197, v55, v171, v197
	v_and_b32_e32 v188, s61, v56
	v_and_b32_e32 v56, s62, v56
	v_and_b32_e32 v189, s61, v57
	v_and_b32_e32 v57, s62, v57
	v_lshl_add_u32 v160, v196, 4, v197
	v_and_b32_e32 v190, s61, v58
	v_and_b32_e32 v58, s62, v58
	v_and_b32_e32 v191, s61, v59
	v_and_b32_e32 v59, s62, v59
	v_dot4_i32_i8 v198, v188, v164, 0
	v_dot4_i32_i8 v199, v56, v165, 0
	v_dot4_i32_i8 v198, v189, v166, v198
	v_dot4_i32_i8 v199, v57, v167, v199
	v_dot4_i32_i8 v198, v190, v168, v198
	v_dot4_i32_i8 v199, v58, v169, v199
	v_dot4_i32_i8 v198, v191, v170, v198
	v_dot4_i32_i8 v199, v59, v171, v199
	s_waitcnt vmcnt(24)
	v_and_b32_e32 v180, s61, v60
	v_and_b32_e32 v60, s62, v60
	v_and_b32_e32 v181, s61, v61
	v_and_b32_e32 v61, s62, v61
	v_lshl_add_u32 v161, v198, 4, v199
	v_and_b32_e32 v182, s61, v62
	v_and_b32_e32 v62, s62, v62
	v_and_b32_e32 v183, s61, v63
	v_and_b32_e32 v63, s62, v63
	v_dot4_i32_i8 v196, v180, v164, 0
	v_dot4_i32_i8 v197, v60, v165, 0
	v_dot4_i32_i8 v196, v181, v166, v196
	v_dot4_i32_i8 v197, v61, v167, v197
	v_dot4_i32_i8 v196, v182, v168, v196
	v_dot4_i32_i8 v197, v62, v169, v197
	v_dot4_i32_i8 v196, v183, v170, v196
	v_dot4_i32_i8 v197, v63, v171, v197
	v_and_b32_e32 v188, s61, v64
	v_and_b32_e32 v64, s62, v64
	v_and_b32_e32 v189, s61, v65
	v_and_b32_e32 v65, s62, v65
	v_lshl_add_u32 v162, v196, 4, v197
	v_and_b32_e32 v190, s61, v66
	v_and_b32_e32 v66, s62, v66
	v_and_b32_e32 v191, s61, v67
	v_and_b32_e32 v67, s62, v67
	v_dot4_i32_i8 v198, v188, v164, 0
	v_dot4_i32_i8 v199, v64, v165, 0
	v_dot4_i32_i8 v198, v189, v166, v198
	v_dot4_i32_i8 v199, v65, v167, v199
	v_dot4_i32_i8 v198, v190, v168, v198
	v_dot4_i32_i8 v199, v66, v169, v199
	v_dot4_i32_i8 v198, v191, v170, v198
	v_dot4_i32_i8 v199, v67, v171, v199
	s_add_i32 s93, s93, s39
	global_load_dwordx4 v[164:167], v2, s[44:45]
	global_load_dwordx4 v[168:171], v2, s[44:45] offset:16
	s_nop 1
	v_lshl_add_u32 v163, v198, 4, v199
	v_cndmask_b32_e64 v200, v148, v152, s[82:83]
	v_cndmask_b32_e64 v201, v152, v148, s[82:83]
	v_cndmask_b32_e64 v202, v149, v153, s[82:83]
	v_cndmask_b32_e64 v203, v153, v149, s[82:83]
	v_cndmask_b32_e64 v204, v150, v154, s[82:83]
	v_cndmask_b32_e64 v205, v154, v150, s[82:83]
	v_cndmask_b32_e64 v206, v151, v155, s[82:83]
	v_cndmask_b32_e64 v207, v155, v151, s[82:83]
	v_cndmask_b32_e64 v208, v156, v160, s[82:83]
	v_cndmask_b32_e64 v209, v160, v156, s[82:83]
	v_cndmask_b32_e64 v210, v157, v161, s[82:83]
	v_cndmask_b32_e64 v211, v161, v157, s[82:83]
	v_cndmask_b32_e64 v212, v158, v162, s[82:83]
	v_cndmask_b32_e64 v213, v162, v158, s[82:83]
	v_cndmask_b32_e64 v214, v159, v163, s[82:83]
	v_cndmask_b32_e64 v215, v163, v159, s[82:83]
	s_nop 1
	v_add_u32_dpp v200, v201, v200 row_half_mirror row_mask:0xf bank_mask:0xf bound_ctrl:1
	v_add_u32_dpp v202, v203, v202 row_half_mirror row_mask:0xf bank_mask:0xf bound_ctrl:1
	v_add_u32_dpp v204, v205, v204 row_half_mirror row_mask:0xf bank_mask:0xf bound_ctrl:1
	v_add_u32_dpp v206, v207, v206 row_half_mirror row_mask:0xf bank_mask:0xf bound_ctrl:1
	v_add_u32_dpp v208, v209, v208 row_half_mirror row_mask:0xf bank_mask:0xf bound_ctrl:1
	v_add_u32_dpp v210, v211, v210 row_half_mirror row_mask:0xf bank_mask:0xf bound_ctrl:1
	v_add_u32_dpp v212, v213, v212 row_half_mirror row_mask:0xf bank_mask:0xf bound_ctrl:1
	v_add_u32_dpp v214, v215, v214 row_half_mirror row_mask:0xf bank_mask:0xf bound_ctrl:1
	v_cndmask_b32_e64 v216, v200, v204, s[84:85]
	v_cndmask_b32_e64 v217, v204, v200, s[84:85]
	v_cndmask_b32_e64 v218, v202, v206, s[84:85]
	v_cndmask_b32_e64 v219, v206, v202, s[84:85]
	v_cndmask_b32_e64 v220, v208, v212, s[84:85]
	v_cndmask_b32_e64 v221, v212, v208, s[84:85]
	v_cndmask_b32_e64 v222, v210, v214, s[84:85]
	v_cndmask_b32_e64 v223, v214, v210, s[84:85]
	s_nop 1
	v_add_u32_dpp v216, v217, v216 quad_perm:[2,3,0,1] row_mask:0xf bank_mask:0xf bound_ctrl:1
	v_add_u32_dpp v218, v219, v218 quad_perm:[2,3,0,1] row_mask:0xf bank_mask:0xf bound_ctrl:1
	v_add_u32_dpp v220, v221, v220 quad_perm:[2,3,0,1] row_mask:0xf bank_mask:0xf bound_ctrl:1
	v_add_u32_dpp v222, v223, v222 quad_perm:[2,3,0,1] row_mask:0xf bank_mask:0xf bound_ctrl:1
	v_cndmask_b32_e64 v224, v216, v218, s[86:87]
	v_cndmask_b32_e64 v225, v218, v216, s[86:87]
	v_cndmask_b32_e64 v226, v220, v222, s[86:87]
	v_cndmask_b32_e64 v227, v222, v220, s[86:87]
	s_nop 1
	v_add_u32_dpp v224, v225, v224 quad_perm:[1,0,3,2] row_mask:0xf bank_mask:0xf bound_ctrl:1
	v_add_u32_dpp v226, v227, v226 quad_perm:[1,0,3,2] row_mask:0xf bank_mask:0xf bound_ctrl:1
	s_nop 1
	global_store_dword v3, v224, s[46:47] nt
	global_store_dword v3, v226, s[46:47] offset:32 nt
	s_add_u32 s46, s46, s48
	s_addc_u32 s47, s47, 0
	s_cmp_lt_i32 s93, 0x8000
	s_cbranch_scc0 .Lmy_u_done
; __device__ __forceinline__ void u_compute(const u32x4 (&w)[16], const PeerVisit& v, int* pd, int lane) {
;     ...
;     for (int it = 0; it < 16; ++it) {
;         int tl = 0, th = 0;
;         tl = __builtin_amdgcn_sdot4((int)(w[it].x & 0x0F0F0F0Fu), (int)v.x.x, tl, false);  th = __builtin_amdgcn_sdot4((int)(w[it].x & 0xF0F0F0F0u), (int)v.x.y, th, false);
;         tl = __builtin_amdgcn_sdot4((int)(w[it].y & 0x0F0F0F0Fu), (int)v.x.z, tl, false);  th = __builtin_amdgcn_sdot4((int)(w[it].y & 0xF0F0F0F0u), (int)v.x.w, th, false);
;         tl = __builtin_amdgcn_sdot4((int)(w[it].z & 0x0F0F0F0Fu), (int)v.x2.x, tl, false); th = __builtin_amdgcn_sdot4((int)(w[it].z & 0xF0F0F0F0u), (int)v.x2.y, th, false);
;         tl = __builtin_amdgcn_sdot4((int)(w[it].w & 0x0F0F0F0Fu), (int)v.x2.z, tl, false); th = __builtin_amdgcn_sdot4((int)(w[it].w & 0xF0F0F0F0u), (int)v.x2.w, th, false);
;         const int t = tl * 16 + th;
;         d[it] = dpp_add8(t);
;     }
; template <bool VPASS>
; __device__ __forceinline__ void peer_pass(Frame& F, int c, int rank, int nblk) {
;     ...
;     for (int v = 0; v < nvis; v += 2) {
;         const int tok = t0 + v * step;
;         asm volatile("" : "+v"(lane));
;         PeerVisit vn = va;
;         if (v + 1 < nvis) rows16_load(wb, T, vb, lane);
;         if (v + 2 < nvis) vn = visit_load<VPASS>(F.ws, FQc, tok + 2 * step, lane);
;         if (VPASS) v_compute(wa, va, PO + (size_t)tok * D, lane); else u_compute(wa, va, PD + (size_t)tok * 128, lane);
;         if (v + 1 < nvis) {
;             PeerVisit vm = vb;
;             if (v + 2 < nvis) rows16_load(wa, T, vn, lane);
;             if (v + 3 < nvis) vm = visit_load<VPASS>(F.ws, FQc, tok + 3 * step, lane);
;             if (VPASS) v_compute(wb, vb, PO + (size_t)(tok + step) * D, lane); else u_compute(wb, vb, PD + (size_t)(tok + step) * 128, lane);
	s_waitcnt vmcnt(20)
	v_lshl_add_u32 v180, v132, 7, v1
	v_lshl_add_u32 v181, v133, 7, v1
	v_lshl_add_u32 v182, v134, 7, v1
	v_lshl_add_u32 v183, v135, 7, v1
	v_lshl_add_u32 v184, v136, 7, v1
	v_lshl_add_u32 v185, v137, 7, v1
	v_lshl_add_u32 v186, v138, 7, v1
	v_lshl_add_u32 v187, v139, 7, v1
	v_lshl_add_u32 v188, v140, 7, v1
	v_lshl_add_u32 v189, v141, 7, v1
	v_lshl_add_u32 v190, v142, 7, v1
	v_lshl_add_u32 v191, v143, 7, v1
	v_lshl_add_u32 v192, v144, 7, v1
	v_lshl_add_u32 v193, v145, 7, v1
	v_lshl_add_u32 v194, v146, 7, v1
	v_lshl_add_u32 v195, v147, 7, v1
	s_add_i32 s38, s38, s39
	s_cmp_lt_i32 s38, 0x8000
	s_cselect_b32 s63, s48, 0
	s_cselect_b32 s71, s49, 0
	s_add_u32 s42, s42, s63
	s_addc_u32 s43, s43, 0
	s_add_u32 s44, s44, s71
	s_addc_u32 s45, s45, 0
	global_load_dwordx4 v[132:135], v0, s[42:43]
	global_load_dwordx4 v[136:139], v0, s[42:43] offset:16
	global_load_dwordx4 v[140:143], v0, s[42:43] offset:32
	global_load_dwordx4 v[144:147], v0, s[42:43] offset:48
	global_load_dwordx4 v[4:7], v180, s[40:41]
	global_load_dwordx4 v[8:11], v181, s[40:41]
	global_load_dwordx4 v[12:15], v182, s[40:41]
	global_load_dwordx4 v[16:19], v183, s[40:41]
	global_load_dwordx4 v[20:23], v184, s[40:41]
	global_load_dwordx4 v[24:27], v185, s[40:41]
	global_load_dwordx4 v[28:31], v186, s[40:41]
	global_load_dwordx4 v[32:35], v187, s[40:41]
	global_load_dwordx4 v[36:39], v188, s[40:41]
	global_load_dwordx4 v[40:43], v189, s[40:41]
	global_load_dwordx4 v[44:47], v190, s[40:41]
	global_load_dwordx4 v[48:51], v191, s[40:41]
	global_load_dwordx4 v[52:55], v192, s[40:41]
	global_load_dwordx4 v[56:59], v193, s[40:41]
	global_load_dwordx4 v[60:63], v194, s[40:41]
	global_load_dwordx4 v[64:67], v195, s[40:41]
	s_waitcnt vmcnt(38)
	v_and_b32_e32 v180, s61, v68
	v_and_b32_e32 v68, s62, v68
	v_and_b32_e32 v181, s61, v69
	v_and_b32_e32 v69, s62, v69
	v_and_b32_e32 v182, s61, v70
	v_and_b32_e32 v70, s62, v70
	v_and_b32_e32 v183, s61, v71
	v_and_b32_e32 v71, s62, v71
	v_dot4_i32_i8 v196, v180, v172, 0
	v_dot4_i32_i8 v197, v68, v173, 0
	v_dot4_i32_i8 v196, v181, v174, v196
	v_dot4_i32_i8 v197, v69, v175, v197
	v_dot4_i32_i8 v196, v182, v176, v196
	v_dot4_i32_i8 v197, v70, v177, v197
	v_dot4_i32_i8 v196, v183, v178, v196
	v_dot4_i32_i8 v197, v71, v179, v197
	v_and_b32_e32 v188, s61, v72
	v_and_b32_e32 v72, s62, v72
	v_and_b32_e32 v189, s61, v73
	v_and_b32_e32 v73, s62, v73
	v_lshl_add_u32 v148, v196, 4, v197
	v_and_b32_e32 v190, s61, v74
	v_and_b32_e32 v74, s62, v74
	v_and_b32_e32 v191, s61, v75
	v_and_b32_e32 v75, s62, v75
	v_dot4_i32_i8 v198, v188, v172, 0
	v_dot4_i32_i8 v199, v72, v173, 0
	v_dot4_i32_i8 v198, v189, v174, v198
	v_dot4_i32_i8 v199, v73, v175, v199
	v_dot4_i32_i8 v198, v190, v176, v198
	v_dot4_i32_i8 v199, v74, v177, v199
	v_dot4_i32_i8 v198, v191, v178, v198
	v_dot4_i32_i8 v199, v75, v179, v199
	s_waitcnt vmcnt(36)
	v_and_b32_e32 v180, s61, v76
	v_and_b32_e32 v76, s62, v76
	v_and_b32_e32 v181, s61, v77
	v_and_b32_e32 v77, s62, v77
	v_lshl_add_u32 v149, v198, 4, v199
	v_and_b32_e32 v182, s61, v78
	v_and_b32_e32 v78, s62, v78
	v_and_b32_e32 v183, s61, v79
	v_and_b32_e32 v79, s62, v79
	v_dot4_i32_i8 v196, v180, v172, 0
	v_dot4_i32_i8 v197, v76, v173, 0
	v_dot4_i32_i8 v196, v181, v174, v196
	v_dot4_i32_i8 v197, v77, v175, v197
	v_dot4_i32_i8 v196, v182, v176, v196
	v_dot4_i32_i8 v197, v78, v177, v197
	v_dot4_i32_i8 v196, v183, v178, v196
	v_dot4_i32_i8 v197, v79, v179, v197
	v_and_b32_e32 v188, s61, v80
	v_and_b32_e32 v80, s62, v80
	v_and_b32_e32 v189, s61, v81
	v_and_b32_e32 v81, s62, v81
	v_lshl_add_u32 v150, v196, 4, v197
	v_and_b32_e32 v190, s61, v82
	v_and_b32_e32 v82, s62, v82
	v_and_b32_e32 v191, s61, v83
	v_and_b32_e32 v83, s62, v83
	v_dot4_i32_i8 v198, v188, v172, 0
	v_dot4_i32_i8 v199, v80, v173, 0
	v_dot4_i32_i8 v198, v189, v174, v198
	v_dot4_i32_i8 v199, v81, v175, v199
	v_dot4_i32_i8 v198, v190, v176, v198
	v_dot4_i32_i8 v199, v82, v177, v199
	v_dot4_i32_i8 v198, v191, v178, v198
	v_dot4_i32_i8 v199, v83, v179, v199
	s_waitcnt vmcnt(34)
	v_and_b32_e32 v180, s61, v84
	v_and_b32_e32 v84, s62, v84
	v_and_b32_e32 v181, s61, v85
	v_and_b32_e32 v85, s62, v85
	v_lshl_add_u32 v151, v198, 4, v199
	v_and_b32_e32 v182, s61, v86
	v_and_b32_e32 v86, s62, v86
	v_and_b32_e32 v183, s61, v87
	v_and_b32_e32 v87, s62, v87
	v_dot4_i32_i8 v196, v180, v172, 0
	v_dot4_i32_i8 v197, v84, v173, 0
	v_dot4_i32_i8 v196, v181, v174, v196
	v_dot4_i32_i8 v197, v85, v175, v197
	v_dot4_i32_i8 v196, v182, v176, v196
	v_dot4_i32_i8 v197, v86, v177, v197
	v_dot4_i32_i8 v196, v183, v178, v196
	v_dot4_i32_i8 v197, v87, v179, v197
	v_and_b32_e32 v188, s61, v88
	v_and_b32_e32 v88, s62, v88
	v_and_b32_e32 v189, s61, v89
	v_and_b32_e32 v89, s62, v89
	v_lshl_add_u32 v152, v196, 4, v197
	v_and_b32_e32 v190, s61, v90
	v_and_b32_e32 v90, s62, v90
	v_and_b32_e32 v191, s61, v91
	v_and_b32_e32 v91, s62, v91
	v_dot4_i32_i8 v198, v188, v172, 0
	v_dot4_i32_i8 v199, v88, v173, 0
	v_dot4_i32_i8 v198, v189, v174, v198
	v_dot4_i32_i8 v199, v89, v175, v199
	v_dot4_i32_i8 v198, v190, v176, v198
	v_dot4_i32_i8 v199, v90, v177, v199
	v_dot4_i32_i8 v198, v191, v178, v198
	v_dot4_i32_i8 v199, v91, v179, v199
	s_waitcnt vmcnt(32)
; __device__ __forceinline__ void u_compute(const u32x4 (&w)[16], const PeerVisit& v, int* pd, int lane) {
;     ...
;     for (int it = 0; it < 16; ++it) {
;         int tl = 0, th = 0;
;         tl = __builtin_amdgcn_sdot4((int)(w[it].x & 0x0F0F0F0Fu), (int)v.x.x, tl, false);  th = __builtin_amdgcn_sdot4((int)(w[it].x & 0xF0F0F0F0u), (int)v.x.y, th, false);
;         tl = __builtin_amdgcn_sdot4((int)(w[it].y & 0x0F0F0F0Fu), (int)v.x.z, tl, false);  th = __builtin_amdgcn_sdot4((int)(w[it].y & 0xF0F0F0F0u), (int)v.x.w, th, false);
;         tl = __builtin_amdgcn_sdot4((int)(w[it].z & 0x0F0F0F0Fu), (int)v.x2.x, tl, false); th = __builtin_amdgcn_sdot4((int)(w[it].z & 0xF0F0F0F0u), (int)v.x2.y, th, false);
;         tl = __builtin_amdgcn_sdot4((int)(w[it].w & 0x0F0F0F0Fu), (int)v.x2.z, tl, false); th = __builtin_amdgcn_sdot4((int)(w[it].w & 0xF0F0F0F0u), (int)v.x2.w, th, false);
;         const int t = tl * 16 + th;
;         d[it] = dpp_add8(t);
;     }
	v_and_b32_e32 v180, s61, v92
	v_and_b32_e32 v92, s62, v92
	v_and_b32_e32 v181, s61, v93
	v_and_b32_e32 v93, s62, v93
	v_lshl_add_u32 v153, v198, 4, v199
	v_and_b32_e32 v182, s61, v94
	v_and_b32_e32 v94, s62, v94
	v_and_b32_e32 v183, s61, v95
	v_and_b32_e32 v95, s62, v95
	v_dot4_i32_i8 v196, v180, v172, 0
	v_dot4_i32_i8 v197, v92, v173, 0
	v_dot4_i32_i8 v196, v181, v174, v196
	v_dot4_i32_i8 v197, v93, v175, v197
	v_dot4_i32_i8 v196, v182, v176, v196
	v_dot4_i32_i8 v197, v94, v177, v197
	v_dot4_i32_i8 v196, v183, v178, v196
	v_dot4_i32_i8 v197, v95, v179, v197
	v_and_b32_e32 v188, s61, v96
	v_and_b32_e32 v96, s62, v96
	v_and_b32_e32 v189, s61, v97
	v_and_b32_e32 v97, s62, v97
	v_lshl_add_u32 v154, v196, 4, v197
	v_and_b32_e32 v190, s61, v98
	v_and_b32_e32 v98, s62, v98
	v_and_b32_e32 v191, s61, v99
	v_and_b32_e32 v99, s62, v99
	v_dot4_i32_i8 v198, v188, v172, 0
	v_dot4_i32_i8 v199, v96, v173, 0
	v_dot4_i32_i8 v198, v189, v174, v198
	v_dot4_i32_i8 v199, v97, v175, v199
	v_dot4_i32_i8 v198, v190, v176, v198
	v_dot4_i32_i8 v199, v98, v177, v199
	v_dot4_i32_i8 v198, v191, v178, v198
	v_dot4_i32_i8 v199, v99, v179, v199
	s_waitcnt vmcnt(30)
	v_and_b32_e32 v180, s61, v100
	v_and_b32_e32 v100, s62, v100
	v_and_b32_e32 v181, s61, v101
	v_and_b32_e32 v101, s62, v101
	v_lshl_add_u32 v155, v198, 4, v199
	v_and_b32_e32 v182, s61, v102
	v_and_b32_e32 v102, s62, v102
	v_and_b32_e32 v183, s61, v103
	v_and_b32_e32 v103, s62, v103
	v_dot4_i32_i8 v196, v180, v172, 0
	v_dot4_i32_i8 v197, v100, v173, 0
	v_dot4_i32_i8 v196, v181, v174, v196
	v_dot4_i32_i8 v197, v101, v175, v197
	v_dot4_i32_i8 v196, v182, v176, v196
	v_dot4_i32_i8 v197, v102, v177, v197
	v_dot4_i32_i8 v196, v183, v178, v196
	v_dot4_i32_i8 v197, v103, v179, v197
	v_and_b32_e32 v188, s61, v104
	v_and_b32_e32 v104, s62, v104
	v_and_b32_e32 v189, s61, v105
	v_and_b32_e32 v105, s62, v105
	v_lshl_add_u32 v156, v196, 4, v197
	v_and_b32_e32 v190, s61, v106
	v_and_b32_e32 v106, s62, v106
	v_and_b32_e32 v191, s61, v107
	v_and_b32_e32 v107, s62, v107
	v_dot4_i32_i8 v198, v188, v172, 0
	v_dot4_i32_i8 v199, v104, v173, 0
	v_dot4_i32_i8 v198, v189, v174, v198
	v_dot4_i32_i8 v199, v105, v175, v199
	v_dot4_i32_i8 v198, v190, v176, v198
	v_dot4_i32_i8 v199, v106, v177, v199
	v_dot4_i32_i8 v198, v191, v178, v198
	v_dot4_i32_i8 v199, v107, v179, v199
	s_waitcnt vmcnt(28)
	v_and_b32_e32 v180, s61, v108
	v_and_b32_e32 v108, s62, v108
	v_and_b32_e32 v181, s61, v109
	v_and_b32_e32 v109, s62, v109
	v_lshl_add_u32 v157, v198, 4, v199
	v_and_b32_e32 v182, s61, v110
	v_and_b32_e32 v110, s62, v110
	v_and_b32_e32 v183, s61, v111
	v_and_b32_e32 v111, s62, v111
	v_dot4_i32_i8 v196, v180, v172, 0
	v_dot4_i32_i8 v197, v108, v173, 0
	v_dot4_i32_i8 v196, v181, v174, v196
	v_dot4_i32_i8 v197, v109, v175, v197
	v_dot4_i32_i8 v196, v182, v176, v196
	v_dot4_i32_i8 v197, v110, v177, v197
	v_dot4_i32_i8 v196, v183, v178, v196
	v_dot4_i32_i8 v197, v111, v179, v197
	v_and_b32_e32 v188, s61, v112
	v_and_b32_e32 v112, s62, v112
	v_and_b32_e32 v189, s61, v113
	v_and_b32_e32 v113, s62, v113
	v_lshl_add_u32 v158, v196, 4, v197
	v_and_b32_e32 v190, s61, v114
	v_and_b32_e32 v114, s62, v114
	v_and_b32_e32 v191, s61, v115
	v_and_b32_e32 v115, s62, v115
	v_dot4_i32_i8 v198, v188, v172, 0
	v_dot4_i32_i8 v199, v112, v173, 0
	v_dot4_i32_i8 v198, v189, v174, v198
	v_dot4_i32_i8 v199, v113, v175, v199
	v_dot4_i32_i8 v198, v190, v176, v198
	v_dot4_i32_i8 v199, v114, v177, v199
	v_dot4_i32_i8 v198, v191, v178, v198
	v_dot4_i32_i8 v199, v115, v179, v199
	s_waitcnt vmcnt(26)
	v_and_b32_e32 v180, s61, v116
	v_and_b32_e32 v116, s62, v116
	v_and_b32_e32 v181, s61, v117
	v_and_b32_e32 v117, s62, v117
	v_lshl_add_u32 v159, v198, 4, v199
	v_and_b32_e32 v182, s61, v118
	v_and_b32_e32 v118, s62, v118
	v_and_b32_e32 v183, s61, v119
	v_and_b32_e32 v119, s62, v119
	v_dot4_i32_i8 v196, v180, v172, 0
	v_dot4_i32_i8 v197, v116, v173, 0
	v_dot4_i32_i8 v196, v181, v174, v196
	v_dot4_i32_i8 v197, v117, v175, v197
	v_dot4_i32_i8 v196, v182, v176, v196
	v_dot4_i32_i8 v197, v118, v177, v197
	v_dot4_i32_i8 v196, v183, v178, v196
	v_dot4_i32_i8 v197, v119, v179, v197
	v_and_b32_e32 v188, s61, v120
	v_and_b32_e32 v120, s62, v120
	v_and_b32_e32 v189, s61, v121
	v_and_b32_e32 v121, s62, v121
	v_lshl_add_u32 v160, v196, 4, v197
	v_and_b32_e32 v190, s61, v122
	v_and_b32_e32 v122, s62, v122
	v_and_b32_e32 v191, s61, v123
	v_and_b32_e32 v123, s62, v123
	v_dot4_i32_i8 v198, v188, v172, 0
	v_dot4_i32_i8 v199, v120, v173, 0
	v_dot4_i32_i8 v198, v189, v174, v198
	v_dot4_i32_i8 v199, v121, v175, v199
	v_dot4_i32_i8 v198, v190, v176, v198
	v_dot4_i32_i8 v199, v122, v177, v199
	v_dot4_i32_i8 v198, v191, v178, v198
	v_dot4_i32_i8 v199, v123, v179, v199
	s_waitcnt vmcnt(24)
; __device__ __forceinline__ void u_compute(const u32x4 (&w)[16], const PeerVisit& v, int* pd, int lane) {
;     ...
;     for (int it = 0; it < 16; ++it) {
;         int tl = 0, th = 0;
;         tl = __builtin_amdgcn_sdot4((int)(w[it].x & 0x0F0F0F0Fu), (int)v.x.x, tl, false);  th = __builtin_amdgcn_sdot4((int)(w[it].x & 0xF0F0F0F0u), (int)v.x.y, th, false);
;         tl = __builtin_amdgcn_sdot4((int)(w[it].y & 0x0F0F0F0Fu), (int)v.x.z, tl, false);  th = __builtin_amdgcn_sdot4((int)(w[it].y & 0xF0F0F0F0u), (int)v.x.w, th, false);
;         tl = __builtin_amdgcn_sdot4((int)(w[it].z & 0x0F0F0F0Fu), (int)v.x2.x, tl, false); th = __builtin_amdgcn_sdot4((int)(w[it].z & 0xF0F0F0F0u), (int)v.x2.y, th, false);
;         tl = __builtin_amdgcn_sdot4((int)(w[it].w & 0x0F0F0F0Fu), (int)v.x2.z, tl, false); th = __builtin_amdgcn_sdot4((int)(w[it].w & 0xF0F0F0F0u), (int)v.x2.w, th, false);
;         const int t = tl * 16 + th;
;         d[it] = dpp_add8(t);
;     }
;     int v0 = d[0], v1 = d[8];
; #pragma unroll
;     for (int it = 1; it < 8; ++it) { v0 = (sub == it) ? d[it] : v0; v1 = (sub == it) ? d[8 + it] : v1; }
;     __builtin_nontemporal_store(v0, pd + pg * 16 + sub); __builtin_nontemporal_store(v1, pd + pg * 16 + 8 + sub);
; }
	v_and_b32_e32 v180, s61, v124
	v_and_b32_e32 v124, s62, v124
	v_and_b32_e32 v181, s61, v125
	v_and_b32_e32 v125, s62, v125
	v_lshl_add_u32 v161, v198, 4, v199
	v_and_b32_e32 v182, s61, v126
	v_and_b32_e32 v126, s62, v126
	v_and_b32_e32 v183, s61, v127
	v_and_b32_e32 v127, s62, v127
	v_dot4_i32_i8 v196, v180, v172, 0
	v_dot4_i32_i8 v197, v124, v173, 0
	v_dot4_i32_i8 v196, v181, v174, v196
	v_dot4_i32_i8 v197, v125, v175, v197
	v_dot4_i32_i8 v196, v182, v176, v196
	v_dot4_i32_i8 v197, v126, v177, v197
	v_dot4_i32_i8 v196, v183, v178, v196
	v_dot4_i32_i8 v197, v127, v179, v197
	v_and_b32_e32 v188, s61, v128
	v_and_b32_e32 v128, s62, v128
	v_and_b32_e32 v189, s61, v129
	v_and_b32_e32 v129, s62, v129
	v_lshl_add_u32 v162, v196, 4, v197
	v_and_b32_e32 v190, s61, v130
	v_and_b32_e32 v130, s62, v130
	v_and_b32_e32 v191, s61, v131
	v_and_b32_e32 v131, s62, v131
	v_dot4_i32_i8 v198, v188, v172, 0
	v_dot4_i32_i8 v199, v128, v173, 0
	v_dot4_i32_i8 v198, v189, v174, v198
	v_dot4_i32_i8 v199, v129, v175, v199
	v_dot4_i32_i8 v198, v190, v176, v198
	v_dot4_i32_i8 v199, v130, v177, v199
	v_dot4_i32_i8 v198, v191, v178, v198
	v_dot4_i32_i8 v199, v131, v179, v199
	s_add_i32 s93, s93, s39
	global_load_dwordx4 v[172:175], v2, s[44:45]
	global_load_dwordx4 v[176:179], v2, s[44:45] offset:16
	s_nop 1
	v_lshl_add_u32 v163, v198, 4, v199
	v_cndmask_b32_e64 v200, v148, v152, s[82:83]
	v_cndmask_b32_e64 v201, v152, v148, s[82:83]
	v_cndmask_b32_e64 v202, v149, v153, s[82:83]
	v_cndmask_b32_e64 v203, v153, v149, s[82:83]
	v_cndmask_b32_e64 v204, v150, v154, s[82:83]
	v_cndmask_b32_e64 v205, v154, v150, s[82:83]
	v_cndmask_b32_e64 v206, v151, v155, s[82:83]
	v_cndmask_b32_e64 v207, v155, v151, s[82:83]
	v_cndmask_b32_e64 v208, v156, v160, s[82:83]
	v_cndmask_b32_e64 v209, v160, v156, s[82:83]
	v_cndmask_b32_e64 v210, v157, v161, s[82:83]
	v_cndmask_b32_e64 v211, v161, v157, s[82:83]
	v_cndmask_b32_e64 v212, v158, v162, s[82:83]
	v_cndmask_b32_e64 v213, v162, v158, s[82:83]
	v_cndmask_b32_e64 v214, v159, v163, s[82:83]
	v_cndmask_b32_e64 v215, v163, v159, s[82:83]
	s_nop 1
	v_add_u32_dpp v200, v201, v200 row_half_mirror row_mask:0xf bank_mask:0xf bound_ctrl:1
	v_add_u32_dpp v202, v203, v202 row_half_mirror row_mask:0xf bank_mask:0xf bound_ctrl:1
	v_add_u32_dpp v204, v205, v204 row_half_mirror row_mask:0xf bank_mask:0xf bound_ctrl:1
	v_add_u32_dpp v206, v207, v206 row_half_mirror row_mask:0xf bank_mask:0xf bound_ctrl:1
	v_add_u32_dpp v208, v209, v208 row_half_mirror row_mask:0xf bank_mask:0xf bound_ctrl:1
	v_add_u32_dpp v210, v211, v210 row_half_mirror row_mask:0xf bank_mask:0xf bound_ctrl:1
	v_add_u32_dpp v212, v213, v212 row_half_mirror row_mask:0xf bank_mask:0xf bound_ctrl:1
	v_add_u32_dpp v214, v215, v214 row_half_mirror row_mask:0xf bank_mask:0xf bound_ctrl:1
	v_cndmask_b32_e64 v216, v200, v204, s[84:85]
	v_cndmask_b32_e64 v217, v204, v200, s[84:85]
	v_cndmask_b32_e64 v218, v202, v206, s[84:85]
	v_cndmask_b32_e64 v219, v206, v202, s[84:85]
	v_cndmask_b32_e64 v220, v208, v212, s[84:85]
	v_cndmask_b32_e64 v221, v212, v208, s[84:85]
	v_cndmask_b32_e64 v222, v210, v214, s[84:85]
	v_cndmask_b32_e64 v223, v214, v210, s[84:85]
	s_nop 1
	v_add_u32_dpp v216, v217, v216 quad_perm:[2,3,0,1] row_mask:0xf bank_mask:0xf bound_ctrl:1
	v_add_u32_dpp v218, v219, v218 quad_perm:[2,3,0,1] row_mask:0xf bank_mask:0xf bound_ctrl:1
	v_add_u32_dpp v220, v221, v220 quad_perm:[2,3,0,1] row_mask:0xf bank_mask:0xf bound_ctrl:1
	v_add_u32_dpp v222, v223, v222 quad_perm:[2,3,0,1] row_mask:0xf bank_mask:0xf bound_ctrl:1
	v_cndmask_b32_e64 v224, v216, v218, s[86:87]
	v_cndmask_b32_e64 v225, v218, v216, s[86:87]
	v_cndmask_b32_e64 v226, v220, v222, s[86:87]
	v_cndmask_b32_e64 v227, v222, v220, s[86:87]
	s_nop 1
	v_add_u32_dpp v224, v225, v224 quad_perm:[1,0,3,2] row_mask:0xf bank_mask:0xf bound_ctrl:1
	v_add_u32_dpp v226, v227, v226 quad_perm:[1,0,3,2] row_mask:0xf bank_mask:0xf bound_ctrl:1
	s_nop 1
	global_store_dword v3, v224, s[46:47] nt
	global_store_dword v3, v226, s[46:47] offset:32 nt
	s_add_u32 s46, s46, s48
	s_addc_u32 s47, s47, 0
	s_cmp_lt_i32 s93, 0x8000
	s_cbranch_scc0 .Lmy_u_done
	s_waitcnt vmcnt(20)
	s_branch .Lmy_u_loop
.Lmy_u_done:
.LBB0_2020:
	s_and_b64 vcc, exec, s[52:53]
	s_mov_b64 s[40:41], 0
	s_cbranch_vccnz .LBB0_2022
	v_mbcnt_lo_u32_b32 v0, -1, 0
	v_mbcnt_hi_u32_b32 v0, -1, v0
	s_nop 0
	v_cmp_eq_u32_e32 vcc, 0, v0
	s_and_b64 s[40:41], vcc, exec
